# scan: sample loads issued at start of even chunks; RWKV waves stage all RWKV operands by LDS-DMA so the critical GDN waves do no staging
# speedup vs baseline: 1.0348x; 1.0072x over previous
.LBB0_1232:
	v_readlane_b32 s2, v251, 0
	s_lshl_b32 s0, s2, 3
	v_lshrrev_b32_e32 v33, 3, v219
	s_cmp_lt_i32 s2, 2
	v_and_b32_e32 v33, 6, v33
	s_cselect_b64 s[44:45], -1, 0
	v_and_or_b32 v120, s0, 8, v33
	s_and_b64 s[0:1], s[44:45], exec
	v_readlane_b32 s0, v252, 22
	v_readlane_b32 s1, v252, 18
	s_cselect_b32 s0, s1, s0
	v_readlane_b32 s3, v251, 5
	v_lshl_or_b32 v106, s0, 4, v120
	s_bfe_u32 s0, s3, 0x20006
	v_readlane_b32 s1, v252, 16
	s_or_b32 s51, s1, s0
	s_cmp_lt_i32 s2, 4
	s_cselect_b64 s[10:11], -1, 0
	s_and_b32 s0, s3, 0xffffff80
	s_cmpk_lg_i32 s0, 0x80
	s_cselect_b64 s[48:49], -1, 0
	s_lshl_b32 s0, s51, 2
	s_and_b32 s1, s0, 0x7c
	v_writelane_b32 v251, s1, 45
	s_and_b32 s0, s0, 60
	v_writelane_b32 v251, s0, 39
	s_mul_i32 s0, s2, 0x4100
	s_add_i32 s0, s0, 0
	v_writelane_b32 v251, s0, 59
	v_lshrrev_b16_e32 v26, 13, v26
	v_readlane_b32 s0, v251, 1
	v_readlane_b32 s1, v251, 2
	s_add_u32 s2, s0, 0x1cc00000
	s_addc_u32 s3, s1, 0
	v_writelane_b32 v250, s2, 24
	v_mul_i32_i24_e32 v33, 0xffffffbb, v26
	v_mul_u32_u24_e32 v122, 0x450, v26
	v_writelane_b32 v250, s3, 25
	s_add_u32 s2, s0, 0x1cc40000
	v_writelane_b32 v250, s2, 34
	s_addc_u32 s2, s1, 0
	v_writelane_b32 v250, s2, 18
	s_add_u32 s2, s0, 0x1cc20000
	s_addc_u32 s3, s1, 0
	v_writelane_b32 v250, s2, 40
	v_lshrrev_b16_sdwa v26, v209, v219 dst_sel:DWORD dst_unused:UNUSED_PAD src0_sel:DWORD src1_sel:BYTE_0
	v_mul_lo_u16_e32 v26, 49, v26
	v_writelane_b32 v250, s3, 41
	s_add_u32 s2, s0, 0x18800000
	v_writelane_b32 v250, s2, 12
	s_addc_u32 s2, s1, 0
	v_writelane_b32 v250, s2, 16
	s_add_u32 s2, s0, 0x18400000
	v_writelane_b32 v250, s2, 32
	s_addc_u32 s2, s1, 0
	v_writelane_b32 v250, s2, 8
	s_add_u32 s2, s0, 0x18200000
	v_writelane_b32 v250, s2, 14
	s_addc_u32 s2, s1, 0
	v_writelane_b32 v250, s2, 22
	s_add_u32 s2, s0, 0x17a00000
	v_writelane_b32 v250, s2, 38
	s_addc_u32 s2, s1, 0
	v_writelane_b32 v250, s2, 10
	s_add_u32 s2, s0, 0x1b600000
	v_writelane_b32 v250, s2, 30
	s_addc_u32 s2, s1, 0
	v_writelane_b32 v250, s2, 36
	s_add_u32 s2, s0, 0x18a00000
	v_writelane_b32 v250, s2, 20
	s_addc_u32 s2, s1, 0
	s_add_u32 s0, s0, 0x15c00000
	v_writelane_b32 v251, s0, 61
	s_addc_u32 s0, s1, 0
	v_writelane_b32 v250, s2, 26
	v_writelane_b32 v251, s0, 63
	v_lshrrev_b16_e32 v26, 10, v26
	s_movk_i32 s1, 0xffbb
	s_movk_i32 s2, 0x450
	s_movk_i32 s0, 0xffac
	v_mul_i32_i24_e32 v45, 0xffffffac, v26
	v_mul_u32_u24_e32 v123, 0x540, v26
	v_mul_i32_i24_sdwa v26, v29, s1 dst_sel:DWORD dst_unused:UNUSED_PAD src0_sel:WORD_1 src1_sel:DWORD
	v_mul_u32_u24_sdwa v124, v29, s2 dst_sel:DWORD dst_unused:UNUSED_PAD src0_sel:WORD_1 src1_sel:DWORD
	v_mul_i32_i24_sdwa v29, v30, s0 dst_sel:DWORD dst_unused:UNUSED_PAD src0_sel:WORD_1 src1_sel:DWORD
	s_movk_i32 s0, 0x540
	v_mul_u32_u24_sdwa v125, v30, s0 dst_sel:DWORD dst_unused:UNUSED_PAD src0_sel:WORD_1 src1_sel:DWORD
	v_mul_i32_i24_sdwa v30, v34, s1 dst_sel:DWORD dst_unused:UNUSED_PAD src0_sel:WORD_1 src1_sel:DWORD
	v_mul_u32_u24_sdwa v126, v34, s2 dst_sel:DWORD dst_unused:UNUSED_PAD src0_sel:WORD_1 src1_sel:DWORD
	v_lshrrev_b32_e32 v34, 17, v35
	v_mul_i32_i24_e32 v35, 0xffffffac, v34
	v_mul_u32_u24_e32 v127, 0x540, v34
	v_mul_i32_i24_sdwa v34, v38, s1 dst_sel:DWORD dst_unused:UNUSED_PAD src0_sel:WORD_1 src1_sel:DWORD
	v_mul_u32_u24_sdwa v128, v38, s2 dst_sel:DWORD dst_unused:UNUSED_PAD src0_sel:WORD_1 src1_sel:DWORD
	v_lshrrev_b32_e32 v38, 17, v39
	v_and_b32_e32 v109, 15, v219
	v_mul_i32_i24_e32 v39, 0xffffffac, v38
	v_mul_u32_u24_e32 v129, 0x540, v38
	v_mul_u32_u24_e32 v38, 0x3b6, v107
	v_mul_i32_i24_sdwa v130, v38, s1 dst_sel:DWORD dst_unused:UNUSED_PAD src0_sel:WORD_1 src1_sel:DWORD
	v_cmp_eq_u32_e64 s[0:1], 0, v109
	v_cmp_gt_u32_e64 s[34:35], s2, v107
	v_mul_u32_u24_sdwa v131, v38, s2 dst_sel:DWORD dst_unused:UNUSED_PAD src0_sel:WORD_1 src1_sel:DWORD
	v_writelane_b32 v251, s0, 33
	v_cndmask_b32_e64 v33, v33, v45, s[6:7]
	v_add_lshl_u32 v136, v33, v0, 4
	v_writelane_b32 v251, s1, 34
	v_readlane_b32 s0, v252, 41
	v_readlane_b32 s2, v251, 47
	v_cndmask_b32_e64 v0, v26, v29, s[6:7]
	v_readlane_b32 s3, v251, 48
	s_add_u32 s0, s2, s0
	v_add_lshl_u32 v137, v0, v28, 4
	s_addc_u32 s1, s3, 0
	v_lshlrev_b32_e32 v28, 2, v106
	v_mov_b32_e32 v29, v1
	v_lshrrev_b16_e32 v38, 2, v43
	v_lshl_add_u64 v[110:111], s[0:1], 0, v[28:29]
	s_lshl_b32 s0, s26, 2
	v_readlane_b32 s2, v251, 37
	v_mul_u32_u24_e32 v38, 0x6187, v38
	v_readlane_b32 s3, v251, 38
	s_add_u32 s0, s2, s0
	v_lshrrev_b32_e32 v38, 19, v38
	v_cndmask_b32_e64 v0, v30, v35, s[6:7]
	s_addc_u32 s1, s3, 0
	v_mul_i32_i24_e32 v132, 0xffffffac, v41
	v_mul_u32_u24_e32 v133, 0x540, v41
	v_mul_i32_i24_e32 v41, 0xffffffac, v38
	v_add_lshl_u32 v140, v0, v32, 4
	v_cndmask_b32_e64 v0, v34, v39, s[6:7]
	v_lshl_add_u64 v[112:113], s[0:1], 0, v[28:29]
	v_mov_b32_e32 v28, v1
	v_writelane_b32 v251, s44, 55
	v_mul_u32_u24_e32 v134, 0x540, v38
	v_add_lshl_u32 v135, v41, v43, 4
	v_add_lshl_u32 v141, v0, v37, 4
	v_add_u32_e32 v144, 0x10000, v40
	v_add_u32_e32 v145, 0x10000, v36
	v_add_u32_e32 v146, 0x10000, v31
	v_add_u32_e32 v147, 0x10000, v27
	v_mov_b32_e32 v26, v1
	v_mov_b32_e32 v27, v1
	v_mov_b64_e32 v[32:33], v[28:29]
	v_mov_b64_e32 v[36:37], v[28:29]
	v_mov_b64_e32 v[40:41], v[28:29]
	v_writelane_b32 v251, s45, 56
	v_lshlrev_b32_e32 v121, 5, v109
	v_lshlrev_b32_e32 v108, 4, v109
	s_mov_b32 s57, 0
	v_cmp_eq_u32_e64 s[86:87], 1, v109
	v_cmp_eq_u32_e64 s[88:89], 2, v109
	v_cmp_eq_u32_e64 s[72:73], 3, v109
	v_cmp_eq_u32_e64 s[80:81], 4, v109
	v_cmp_eq_u32_e64 s[78:79], 5, v109
	v_cmp_eq_u32_e64 s[74:75], 6, v109
	v_cmp_eq_u32_e64 s[76:77], 7, v109
	v_cmp_eq_u32_e64 s[28:29], 8, v109
	v_cmp_eq_u32_e64 s[82:83], 9, v109
	v_cmp_eq_u32_e64 s[84:85], 10, v109
	v_cmp_eq_u32_e64 s[36:37], 11, v109
	v_cmp_eq_u32_e64 s[66:67], 12, v109
	v_cmp_eq_u32_e64 s[68:69], 13, v109
	v_cmp_eq_u32_e64 s[42:43], 14, v109
	v_cmp_eq_u32_e64 s[70:71], 15, v109
	v_add_u32_e32 v114, s18, v109
	v_add_u32_e32 v142, 0x10000, v44
	v_add_u32_e32 v143, 0x10000, v42
	s_mov_b32 s56, 0
	s_mov_b32 s12, 0
	v_mov_b64_e32 v[30:31], v[26:27]
	v_mov_b64_e32 v[34:35], v[26:27]
	v_mov_b64_e32 v[38:39], v[26:27]
	s_mov_b32 s13, 0
	v_writelane_b32 v251, s34, 41
	s_nop 1
	v_writelane_b32 v251, s35, 42
	v_readlane_b32 s0, v251, 0
	v_lshlrev_b32_e32 v0, 2, v219
	s_cmp_lt_u32 s0, 2
	s_cbranch_scc0 .Lxch_nopub
	v_add_u32_e32 v0, 0x13200, v0
	ds_write_b32 v0, v147
	ds_write_b32 v0, v146 offset:512
	ds_write_b32 v0, v145 offset:1024
	ds_write_b32 v0, v144 offset:1536
	ds_write_b32 v0, v143 offset:2048
	ds_write_b32 v0, v142 offset:2560
	s_waitcnt lgkmcnt(0)
.Lxch_nopub:
	s_barrier
	s_and_b32 s1, s0, 6
	s_cmp_eq_u32 s1, 2
	s_cbranch_scc0 .Lxch_done
	v_add_u32_e32 v0, 0x13000, v0
	ds_read_b32 v226, v0
	ds_read_b32 v227, v0 offset:512
	ds_read_b32 v228, v0 offset:1024
	ds_read_b32 v229, v0 offset:1536
	ds_read_b32 v230, v0 offset:2048
	ds_read_b32 v231, v0 offset:2560
	s_waitcnt lgkmcnt(0)
.Lxch_done:
	s_cmp_lg_u32 s57, 0x7f0000
	s_cselect_b64 s[94:95], -1, 0
	s_cmp_eq_u32 s57, 0x7f0000
	s_cbranch_scc1 .LBB0_1234
.LBB0_1233:
	s_and_b64 vcc, exec, s[10:11]
	s_cbranch_vccz .Lsc_top_vgpr
	v_readlane_b32 s4, v251, 0
	s_and_b32 s0, s13, 1
	s_xor_b32 s0, s0, 1
	s_mul_i32 s0, s0, 0x9900
	s_cmp_lt_u32 s4, 2
	s_cbranch_scc1 .LBB0_1234
	s_lshl_b32 s5, s4, 10
	s_add_i32 s5, s0, s5
	s_add_i32 s0, s5, 0xfffff800
	v_add_u32_e32 v0, s57, v147
	s_add_i32 m0, s5, 0x0
	s_nop 0
	global_load_lds_dwordx4 v0, s[16:17]
	v_add_u32_e32 v6, s57, v226
	s_add_i32 m0, s0, 0x0
	s_nop 0
	global_load_lds_dwordx4 v6, s[16:17]
	v_add_u32_e32 v0, s57, v146
	s_add_i32 m0, s5, 0x1000
	s_nop 0
	global_load_lds_dwordx4 v0, s[16:17]
	v_add_u32_e32 v6, s57, v227
	s_add_i32 m0, s0, 0x1000
	s_nop 0
	global_load_lds_dwordx4 v6, s[16:17]
	v_add_u32_e32 v0, s57, v145
	s_add_i32 m0, s5, 0x2000
	s_nop 0
	global_load_lds_dwordx4 v0, s[16:17]
	v_add_u32_e32 v6, s57, v228
	s_add_i32 m0, s0, 0x2000
	s_nop 0
	global_load_lds_dwordx4 v6, s[16:17]
	v_add_u32_e32 v0, s57, v144
	s_add_i32 m0, s5, 0x3000
	s_nop 0
	global_load_lds_dwordx4 v0, s[16:17]
	v_add_u32_e32 v6, s57, v229
	s_add_i32 m0, s0, 0x3000
	s_nop 0
	global_load_lds_dwordx4 v6, s[16:17]
	v_add_u32_e32 v0, s57, v143
	s_add_i32 m0, s5, 0x4000
	s_nop 0
	global_load_lds_dwordx4 v0, s[16:17]
	v_add_u32_e32 v6, s57, v230
	s_add_i32 m0, s0, 0x4000
	s_nop 0
	global_load_lds_dwordx4 v6, s[16:17]
	s_cmp_eq_u32 s4, 2
	s_cbranch_scc0 .LBB0_1234
	v_add_u32_e32 v0, s57, v231
	s_add_i32 m0, s0, 0x5000
	s_nop 0
	global_load_lds_dwordx4 v0, s[16:17]
	s_branch .LBB0_1234

.LBB0_1241:
	s_add_i32 s13, s13, 1
	s_branch .LBB0_1787

.LBB0_1249:
	v_mov_b32_e32 v115, v138
	s_cmp_eq_u32 s0, 0
	s_cbranch_scc0 .Lsu_odd
	v_readlane_b32 s0, v251, 12
	v_readlane_b32 s1, v251, 13
	s_andn2_b64 vcc, exec, s[0:1]
	s_cbranch_vccnz .LBB0_1786
	s_and_b32 s0, s13, 7
	s_cmp_eq_u32 s0, 2
	s_cbranch_scc0 .LBB0_1786
	s_cmpk_lt_u32 s13, 0x70
	s_cbranch_scc0 .LBB0_1786
	s_branch .LBB0_1258
.Lsu_odd:
	s_and_b32 s0, s56, 0xfc00
	s_add_i32 s0, s0, s51
	v_and_b32_e32 v54, 15, v115
	s_cmp_lg_u32 s57, 0x7f0000
	s_cbranch_scc1 .Lsu_w6
	s_waitcnt vmcnt(0)

.LBB0_1788:
	global_store_dwordx2 v[60:61], v[58:59], off
	s_waitcnt vmcnt(1)
	s_barrier
	s_branch .Lsc_after_bar

.Lsc_after_bar:
	s_addk_i32 s12, 0x80
	s_addk_i32 s56, 0x200
	s_add_i32 s57, s57, 0x10000
	s_cmp_eq_u32 s57, 0x800000
	v_add_u32_e32 v114, 16, v114
	s_cbranch_scc1 .LBB0_1799
	v_mov_b64_e32 v[26:27], v[42:43]
	v_mov_b64_e32 v[30:31], v[50:51]
	v_mov_b64_e32 v[34:35], v[46:47]
	v_mov_b64_e32 v[38:39], v[54:55]
	v_mov_b64_e32 v[28:29], v[44:45]
	v_mov_b64_e32 v[32:33], v[52:53]
	v_mov_b64_e32 v[36:37], v[48:49]
	v_mov_b64_e32 v[40:41], v[56:57]
	s_cmp_lg_u32 s57, 0x7f0000
	s_cselect_b64 s[94:95], -1, 0
	s_cmp_eq_u32 s57, 0x7f0000
	s_cbranch_scc1 .LBB0_1234
	s_branch .LBB0_1233
